# k16
# baseline (speedup 1.0000x reference)
; __device__ __forceinline__ unsigned pack2(float lo, float hi) { unsigned r; asm volatile("v_cvt_pk_bf16_f32 %0, %1, %2" : "=v"(r) : "v"(lo), "v"(hi)); return r; }
; __device__ __forceinline__ void tr_tile(const float* __restrict__ src, int ldsrc, const float* __restrict__ gain, u16* __restrict__ dst, int lddst,
;                                         int k0, int n0, int mode, float* T) {
;     ...
;   for (int i = 0; i < 8; ++i) {
;     const int k = (tid >> 6) + 8 * i;
;     const float g = gain ? gain[k0 + k] : 1.0f;
; #pragma unroll
;     for (int e2 = 0; e2 < 4; ++e2) T[k * 257 + n4 + ((e2 + rot) & 3)] = v[i][e2] * g;
;   }
;   __syncthreads();
; #pragma unroll
;   for (int q = 0; q < 4; ++q) {
;     const int n = (tid >> 3) + 64 * q, kc = (tid & 7) * 8;
;     const int col = (n & ~3) + (((n & 3) + (n >> 5)) & 3);
;     float f[8];
; #pragma unroll
;     for (int j = 0; j < 8; ++j) f[j] = T[(kc + j) * 257 + col];
;     u32x4 w = {pack2(f[0], f[1]), pack2(f[2], f[3]), pack2(f[4], f[5]), pack2(f[6], f[7])};
;     const int gn = n0 + n;
;     int drow;
;     if (mode == 0) drow = gn;
;     else drow = (gn >> 7) * 256 + (mode - 1) * 128 + (gn & 127);
;     *(u32x4*)(dst + (size_t)drow * lddst + k0 + kc) = w;
;   }
;   __syncthreads();
.LBB0_46:
	v_add3_u32 v4, v9, v34, s48
	s_waitcnt vmcnt(0)
	v_mov_b32_e32 v8, v67
	v_mul_f32_e32 v0, v0, v8
	v_lshl_add_u32 v5, v28, 2, v4
	ds_write_b32 v5, v0
	v_mul_f32_e32 v0, v1, v8
	v_lshl_add_u32 v1, v29, 2, v4
	ds_write_b32 v1, v0
	v_mul_f32_e32 v0, v2, v8
	v_lshl_add_u32 v1, v30, 2, v4
	ds_write_b32 v1, v0
	v_mul_f32_e32 v0, v3, v8
	v_lshl_add_u32 v1, v31, 2, v4
	v_ashrrev_i32_e32 v8, 3, v33
	ds_write_b32 v1, v0
	v_lshrrev_b32_e32 v1, 5, v8
	v_lshlrev_b32_e32 v0, 3, v33
	v_add_u32_e32 v1, v1, v8
	v_lshlrev_b32_e32 v2, 2, v8
	v_and_b32_e32 v0, 56, v0
	v_and_b32_e32 v1, 3, v1
	v_and_b32_e32 v2, -16, v2
	v_mul_u32_u24_e32 v9, 0x404, v0
	v_add_u32_e32 v2, 0, v2
	v_lshlrev_b32_e32 v10, 2, v1
	v_add3_u32 v1, v2, v10, v9
	s_waitcnt lgkmcnt(0)
	s_barrier
	ds_read_b32 v2, v1 offset:1028
	ds_read_b32 v3, v1 offset:3084
	ds_read_b32 v7, v1 offset:5140
	ds_read_b32 v11, v1 offset:7196
	ds_read_b32 v12, v1 offset:6168
	ds_read_b32 v13, v1 offset:4112
	ds_read_b32 v14, v1 offset:2056
	ds_read_b32 v1, v1
	s_cmp_eq_u32 s14, 0
	v_add_u32_e32 v6, s16, v8
	s_cselect_b64 vcc, -1, 0
	s_lshl_b32 s4, s14, 7
	s_add_i32 s14, s4, 0xffffff80
	v_lshlrev_b32_e32 v34, 1, v0
	s_waitcnt lgkmcnt(0)
	v_cvt_pk_bf16_f32 v0, v1, v2
	v_cvt_pk_bf16_f32 v1, v14, v3
	v_cvt_pk_bf16_f32 v2, v13, v7
	v_cvt_pk_bf16_f32 v3, v12, v11
	v_lshlrev_b32_e32 v7, 1, v6
	v_and_b32_e32 v11, 0x7f, v8
	v_and_b32_e32 v7, 0xffffff00, v7
	v_or_b32_e32 v11, s14, v11
	v_add_u32_e32 v7, v7, v11
	v_add_u32_e32 v14, 64, v8
	v_cndmask_b32_e32 v6, v7, v6, vcc
	v_lshrrev_b32_e32 v15, 5, v14
	s_ashr_i32 s27, s26, 31
	v_ashrrev_i32_e32 v7, 31, v6
	v_add_u32_e32 v15, v15, v8
	s_lshl_b64 s[4:5], s[26:27], 1
	v_mul_lo_u32 v12, s24, v7
	v_and_b32_e32 v7, 0x3ffffffc, v14
	v_and_b32_e32 v15, 3, v15
	s_add_u32 s4, s18, s4
	v_lshl_add_u32 v7, v7, 2, 0
	v_lshlrev_b32_e32 v15, 2, v15
	s_addc_u32 s5, s19, s5
	v_add3_u32 v7, v7, v15, v9
	v_lshl_add_u64 v[4:5], s[4:5], 0, v[34:35]
	v_mul_lo_u32 v13, s25, v6
	ds_read_b32 v15, v7 offset:1028
	ds_read_b32 v16, v7 offset:3084
	ds_read_b32 v17, v7 offset:5140
	ds_read_b32 v18, v7 offset:7196
	ds_read_b32 v19, v7 offset:6168
	ds_read_b32 v20, v7 offset:4112
	ds_read_b32 v21, v7 offset:2056
	ds_read_b32 v22, v7
	v_mad_u64_u32 v[6:7], s[4:5], s24, v6, 0
	v_add3_u32 v7, v7, v12, v13
	v_lshl_add_u64 v[6:7], v[6:7], 1, v[4:5]
	global_store_dwordx4 v[6:7], v[0:3], off
	v_add_u32_e32 v6, s16, v14
	v_lshlrev_b32_e32 v7, 1, v6
	v_and_b32_e32 v12, 0x7f, v14
	v_and_b32_e32 v7, 0xffffff00, v7
	v_or_b32_e32 v12, s14, v12
	v_add_u32_e32 v7, v12, v7
	v_cndmask_b32_e32 v6, v7, v6, vcc
	v_ashrrev_i32_e32 v7, 31, v6
	v_add_u32_e32 v14, 0x80, v8
	v_mul_lo_u32 v12, s24, v7
	v_and_b32_e32 v7, 0x3ffffffc, v14
	v_lshl_add_u32 v7, v7, 2, 0
	v_add3_u32 v7, v7, v10, v9
	s_waitcnt lgkmcnt(0)
	v_cvt_pk_bf16_f32 v0, v22, v15
	v_cvt_pk_bf16_f32 v1, v21, v16
	v_cvt_pk_bf16_f32 v2, v20, v17
	v_cvt_pk_bf16_f32 v3, v19, v18
	v_mul_lo_u32 v13, s25, v6
	ds_read_b32 v10, v7 offset:1028
	ds_read_b32 v15, v7 offset:3084
	ds_read_b32 v16, v7 offset:5140
	ds_read_b32 v17, v7 offset:7196
	ds_read_b32 v18, v7 offset:6168
	ds_read_b32 v19, v7 offset:4112
	ds_read_b32 v20, v7 offset:2056
	ds_read_b32 v21, v7
	v_mad_u64_u32 v[6:7], s[4:5], s24, v6, 0
	v_add3_u32 v7, v7, v12, v13
	v_lshl_add_u64 v[6:7], v[6:7], 1, v[4:5]
	global_store_dwordx4 v[6:7], v[0:3], off
	v_add_u32_e32 v6, s16, v14
	v_lshlrev_b32_e32 v7, 1, v6
	v_and_b32_e32 v7, 0xffffff00, v7
	v_add_u32_e32 v7, v7, v11
	v_add_u32_e32 v12, 0xc0, v8
	v_cndmask_b32_e32 v6, v7, v6, vcc
	v_lshrrev_b32_e32 v13, 5, v12
	v_ashrrev_i32_e32 v7, 31, v6
	v_add_u32_e32 v8, v13, v8
	s_waitcnt lgkmcnt(0)
	v_cvt_pk_bf16_f32 v0, v21, v10
	v_mul_lo_u32 v10, s24, v7
	v_and_b32_e32 v7, 0x3ffffffc, v12
	v_and_b32_e32 v8, 3, v8
	v_lshl_add_u32 v7, v7, 2, 0
	v_lshlrev_b32_e32 v8, 2, v8
	v_add3_u32 v7, v7, v8, v9
	v_cvt_pk_bf16_f32 v1, v20, v15
	v_cvt_pk_bf16_f32 v2, v19, v16
	v_cvt_pk_bf16_f32 v3, v18, v17
	ds_read_b32 v8, v7 offset:1028
	ds_read_b32 v9, v7 offset:3084
	ds_read_b32 v13, v7 offset:5140
	ds_read_b32 v14, v7 offset:7196
	ds_read_b32 v15, v7 offset:6168
	ds_read_b32 v16, v7 offset:4112
	ds_read_b32 v17, v7 offset:2056
	ds_read_b32 v18, v7
	v_mul_lo_u32 v11, s25, v6
	v_mad_u64_u32 v[6:7], s[4:5], s24, v6, 0
	v_add3_u32 v7, v7, v10, v11
	v_lshl_add_u64 v[6:7], v[6:7], 1, v[4:5]
	global_store_dwordx4 v[6:7], v[0:3], off
	v_add_u32_e32 v6, s16, v12
	v_lshlrev_b32_e32 v7, 1, v6
	s_waitcnt lgkmcnt(0)
	v_cvt_pk_bf16_f32 v0, v18, v8
	v_and_b32_e32 v8, 0x7f, v12
	v_and_b32_e32 v7, 0xffffff00, v7
	v_or_b32_e32 v8, s14, v8
	v_add_u32_e32 v7, v8, v7
	v_cndmask_b32_e32 v6, v7, v6, vcc
	v_ashrrev_i32_e32 v7, 31, v6
	v_cvt_pk_bf16_f32 v1, v17, v9
	v_mul_lo_u32 v8, s24, v7
	v_mul_lo_u32 v9, s25, v6
	v_mad_u64_u32 v[6:7], s[4:5], s24, v6, 0
	v_add3_u32 v7, v7, v8, v9
	s_add_i32 s49, s49, s37
	s_add_i32 s41, s41, s42
	s_add_i32 s43, s43, s44
	s_add_i32 s45, s45, s46
	v_lshl_add_u64 v[4:5], v[6:7], 1, v[4:5]
	s_cmpk_gt_i32 s49, 0x117f
	v_cvt_pk_bf16_f32 v2, v16, v13
	v_cvt_pk_bf16_f32 v3, v15, v14
	global_store_dwordx4 v[4:5], v[0:3], off
	s_barrier
	s_cbranch_scc1 .LBB0_83

; __device__ __forceinline__ int my_tid() { int t = threadIdx.x; asm volatile("" : "+v"(t)); return t; }
; __device__ __forceinline__ void tr_tile(const float* __restrict__ src, int ldsrc, const float* __restrict__ gain, u16* __restrict__ dst, int lddst,
;                                         int k0, int n0, int mode, float* T) {
;   const int tid = my_tid();
;   const int lane = tid & 63, n4 = lane * 4, rot = lane >> 3;
;   f32x4 v[8];
; #pragma unroll
;   for (int i = 0; i < 8; ++i) v[i] = *(const f32x4*)(src + (size_t)(k0 + (tid >> 6) + 8 * i) * ldsrc + n0 + n4);
; #pragma unroll
;   for (int i = 0; i < 8; ++i) {
;     const int k = (tid >> 6) + 8 * i;
;     const float g = gain ? gain[k0 + k] : 1.0f;
.LBB0_67:
	v_mov_b32_e32 v33, v182
	s_ashr_i32 s17, s16, 31
	s_lshl_b64 s[34:35], s[16:17], 2
	v_lshlrev_b32_e32 v0, 2, v33
	v_ashrrev_i32_e32 v39, 6, v33
	v_and_b32_e32 v38, 0xfc, v0
	v_add_u32_e32 v36, s26, v39
	s_waitcnt lgkmcnt(0)
	s_add_u32 s4, s4, s34
	s_addc_u32 s5, s5, s35
	v_lshlrev_b32_e32 v34, 2, v38
	v_ashrrev_i32_e32 v37, 31, v36
	v_lshl_add_u64 v[0:1], s[4:5], 0, v[34:35]
	v_mul_lo_u32 v4, s30, v37
	v_mul_lo_u32 v5, s31, v36
	v_mad_u64_u32 v[2:3], s[4:5], s30, v36, 0
	v_add3_u32 v3, v3, v4, v5
	v_add_u32_e32 v4, 8, v36
	v_ashrrev_i32_e32 v5, 31, v4
	v_mul_lo_u32 v6, s30, v5
	v_mul_lo_u32 v7, s31, v4
	v_mad_u64_u32 v[4:5], s[4:5], s30, v4, 0
	v_lshl_add_u64 v[2:3], v[2:3], 2, v[0:1]
	v_add3_u32 v5, v5, v6, v7
	v_lshl_add_u64 v[4:5], v[4:5], 2, v[0:1]
	global_load_dwordx4 v[28:31], v[2:3], off
	global_load_dwordx4 v[24:27], v[4:5], off
	v_add_u32_e32 v2, 16, v36
	v_ashrrev_i32_e32 v3, 31, v2
	v_mul_lo_u32 v4, s30, v3
	v_mul_lo_u32 v5, s31, v2
	v_mad_u64_u32 v[2:3], s[4:5], s30, v2, 0
	v_add3_u32 v3, v3, v4, v5
	v_add_u32_e32 v4, 24, v36
	v_ashrrev_i32_e32 v5, 31, v4
	v_mul_lo_u32 v6, s30, v5
	v_mul_lo_u32 v7, s31, v4
	v_mad_u64_u32 v[4:5], s[4:5], s30, v4, 0
	v_lshl_add_u64 v[2:3], v[2:3], 2, v[0:1]
	v_add3_u32 v5, v5, v6, v7
	v_lshl_add_u64 v[4:5], v[4:5], 2, v[0:1]
	global_load_dwordx4 v[20:23], v[2:3], off
	global_load_dwordx4 v[16:19], v[4:5], off
	v_add_u32_e32 v2, 32, v36
	v_ashrrev_i32_e32 v3, 31, v2
	v_mul_lo_u32 v4, s30, v3
	v_mul_lo_u32 v5, s31, v2
	v_mad_u64_u32 v[2:3], s[4:5], s30, v2, 0
	v_add3_u32 v3, v3, v4, v5
	v_add_u32_e32 v4, 40, v36
	v_ashrrev_i32_e32 v5, 31, v4
	v_mul_lo_u32 v6, s30, v5
	v_mul_lo_u32 v7, s31, v4
	v_mad_u64_u32 v[4:5], s[4:5], s30, v4, 0
	v_lshl_add_u64 v[2:3], v[2:3], 2, v[0:1]
	v_add3_u32 v5, v5, v6, v7
	v_lshl_add_u64 v[4:5], v[4:5], 2, v[0:1]
	global_load_dwordx4 v[12:15], v[2:3], off
	global_load_dwordx4 v[8:11], v[4:5], off
	v_add_u32_e32 v2, 48, v36
	v_ashrrev_i32_e32 v3, 31, v2
	v_mul_lo_u32 v4, s30, v3
	v_mul_lo_u32 v5, s31, v2
	v_mad_u64_u32 v[2:3], s[4:5], s30, v2, 0
	v_add3_u32 v3, v3, v4, v5
	v_add_u32_e32 v4, 56, v36
	v_ashrrev_i32_e32 v5, 31, v4
	v_mul_lo_u32 v6, s30, v5
	v_mul_lo_u32 v7, s31, v4
	v_mad_u64_u32 v[4:5], s[4:5], s30, v4, 0
	v_add3_u32 v5, v5, v6, v7
	v_lshl_add_u64 v[2:3], v[2:3], 2, v[0:1]
	v_lshl_add_u64 v[0:1], v[4:5], 2, v[0:1]
	global_load_dwordx4 v[4:7], v[2:3], off
	s_nop 0
	global_load_dwordx4 v[0:3], v[0:1], off
	s_cmp_lg_u64 s[28:29], 0
	v_mov_b32_e32 v40, 1.0
	s_cselect_b64 s[30:31], -1, 0
	s_cmp_eq_u64 s[28:29], 0
	v_lshl_add_u64 v[36:37], v[36:37], 2, s[28:29]
	v_mov_b32_e32 v41, 1.0
	v_mov_b32_e32 v60, 1.0
	v_mov_b32_e32 v61, 1.0
	v_mov_b32_e32 v62, 1.0
	v_mov_b32_e32 v63, 1.0
	v_mov_b32_e32 v64, 1.0
	v_mov_b32_e32 v65, 1.0
	v_mov_b32_e32 v66, 1.0
	v_mov_b32_e32 v67, 1.0
	s_cbranch_scc1 .Lprep_nogain
	global_load_dword v60, v[36:37], off
	global_load_dword v61, v[36:37], off offset:32
	global_load_dword v62, v[36:37], off offset:64
	global_load_dword v63, v[36:37], off offset:96
	global_load_dword v64, v[36:37], off offset:128
	global_load_dword v65, v[36:37], off offset:160
	global_load_dword v66, v[36:37], off offset:192
	global_load_dword v67, v[36:37], off offset:224
.Lprep_nogain:
	s_cbranch_scc1 .LBB0_69
; __device__ __forceinline__ void tr_tile(const float* __restrict__ src, int ldsrc, const float* __restrict__ gain, u16* __restrict__ dst, int lddst,
;                                         int k0, int n0, int mode, float* T) {
;     ...
; #pragma unroll
;   for (int i = 0; i < 8; ++i) {
;     const int k = (tid >> 6) + 8 * i;
;     const float g = gain ? gain[k0 + k] : 1.0f;
; #pragma unroll
;     for (int e2 = 0; e2 < 4; ++e2) T[k * 257 + n4 + ((e2 + rot) & 3)] = v[i][e2] * g;
;   }
.LBB0_69:
	v_lshl_add_u32 v34, v38, 2, 0
	v_mul_lo_u32 v38, v39, s47
	v_add_u32_e32 v39, v34, v38
	s_waitcnt vmcnt(0)
	v_mov_b32_e32 v41, v60
	v_mul_f32_e32 v43, v28, v41
	v_bfe_u32 v28, v33, 3, 2
	v_lshrrev_b32_e32 v42, 3, v33
	v_lshl_add_u32 v44, v28, 2, v39
	ds_write_b32 v44, v43
	v_mul_f32_e32 v43, v29, v41
	v_add_u32_e32 v29, 1, v42
	v_and_b32_e32 v29, 3, v29
	v_lshl_add_u32 v44, v29, 2, v39
	ds_write_b32 v44, v43
	v_mul_f32_e32 v43, v30, v41
	v_mul_f32_e32 v41, v31, v41
	v_add_u32_e32 v31, -1, v42
	v_bitop3_b32 v30, v42, 2, 3 bitop3:0x6c
	v_and_b32_e32 v31, 3, v31
	v_cndmask_b32_e64 v42, 0, 1, s[30:31]
	v_lshl_add_u32 v44, v30, 2, v39
	v_lshl_add_u32 v39, v31, 2, v39
	v_cmp_ne_u32_e64 s[4:5], 1, v42
	s_andn2_b64 vcc, exec, s[30:31]
	ds_write_b32 v44, v43
	ds_write_b32 v39, v41
	s_cbranch_vccnz .LBB0_71
.LBB0_71:
	v_add_u32_e32 v38, 0x2020, v38
	v_add_u32_e32 v39, v34, v38
	s_waitcnt vmcnt(0)
	v_mov_b32_e32 v40, v61
	v_mul_f32_e32 v24, v24, v40
	v_lshl_add_u32 v41, v28, 2, v39
	ds_write_b32 v41, v24
	v_mul_f32_e32 v24, v25, v40
	v_lshl_add_u32 v25, v29, 2, v39
	ds_write_b32 v25, v24
	v_mul_f32_e32 v24, v26, v40
	v_lshl_add_u32 v25, v30, 2, v39
	ds_write_b32 v25, v24
	v_mul_f32_e32 v24, v27, v40
	v_lshl_add_u32 v25, v31, 2, v39
	ds_write_b32 v25, v24
	v_mov_b32_e32 v24, 1.0
	s_and_b64 vcc, exec, s[4:5]
	v_mov_b32_e32 v26, 1.0
	s_cbranch_vccnz .LBB0_73
.LBB0_73:
	v_add_u32_e32 v25, 0x2020, v38
	v_add_u32_e32 v27, v34, v25
	s_waitcnt vmcnt(0)
	v_mov_b32_e32 v26, v62
	v_mul_f32_e32 v20, v20, v26
	v_lshl_add_u32 v38, v28, 2, v27
	ds_write_b32 v38, v20
	v_mul_f32_e32 v20, v21, v26
	v_lshl_add_u32 v21, v29, 2, v27
	ds_write_b32 v21, v20
	v_mul_f32_e32 v20, v22, v26
	v_lshl_add_u32 v21, v30, 2, v27
	ds_write_b32 v21, v20
	v_mul_f32_e32 v20, v23, v26
	v_lshl_add_u32 v21, v31, 2, v27
	s_and_b64 vcc, exec, s[4:5]
	ds_write_b32 v21, v20
	s_cbranch_vccnz .LBB0_75
.LBB0_75:
	v_add_u32_e32 v20, 0x2020, v25
	v_add_u32_e32 v21, v34, v20
	s_waitcnt vmcnt(0)
	v_mov_b32_e32 v24, v63
	v_mul_f32_e32 v16, v16, v24
	v_lshl_add_u32 v22, v28, 2, v21
	ds_write_b32 v22, v16
	v_mul_f32_e32 v16, v17, v24
	v_lshl_add_u32 v17, v29, 2, v21
	ds_write_b32 v17, v16
	v_mul_f32_e32 v16, v18, v24
	v_lshl_add_u32 v17, v30, 2, v21
	ds_write_b32 v17, v16
	v_mul_f32_e32 v16, v19, v24
	v_lshl_add_u32 v17, v31, 2, v21
	ds_write_b32 v17, v16
	v_mov_b32_e32 v16, 1.0
	s_and_b64 vcc, exec, s[4:5]
	v_mov_b32_e32 v18, 1.0
	s_cbranch_vccnz .LBB0_77
.LBB0_77:
	v_add_u32_e32 v17, 0x2020, v20
	v_add_u32_e32 v19, v34, v17
	s_waitcnt vmcnt(0)
	v_mov_b32_e32 v18, v64
	v_mul_f32_e32 v12, v12, v18
	v_lshl_add_u32 v20, v28, 2, v19
	ds_write_b32 v20, v12
	v_mul_f32_e32 v12, v13, v18
	v_lshl_add_u32 v13, v29, 2, v19
	ds_write_b32 v13, v12
	v_mul_f32_e32 v12, v14, v18
	v_lshl_add_u32 v13, v30, 2, v19
	ds_write_b32 v13, v12
	v_mul_f32_e32 v12, v15, v18
	v_lshl_add_u32 v13, v31, 2, v19
	s_and_b64 vcc, exec, s[4:5]
	ds_write_b32 v13, v12
	s_cbranch_vccnz .LBB0_79
.LBB0_79:
	v_add_u32_e32 v12, 0x2020, v17
	v_add_u32_e32 v13, v34, v12
	s_waitcnt vmcnt(0)
	v_mov_b32_e32 v16, v65
	v_mul_f32_e32 v8, v8, v16
	v_lshl_add_u32 v14, v28, 2, v13
	ds_write_b32 v14, v8
	v_mul_f32_e32 v8, v9, v16
	v_lshl_add_u32 v9, v29, 2, v13
	ds_write_b32 v9, v8
	v_mul_f32_e32 v8, v10, v16
	v_lshl_add_u32 v9, v30, 2, v13
	ds_write_b32 v9, v8
	v_mul_f32_e32 v8, v11, v16
	v_lshl_add_u32 v9, v31, 2, v13
	ds_write_b32 v9, v8
	v_mov_b32_e32 v8, 1.0
	s_and_b64 vcc, exec, s[4:5]
	v_mov_b32_e32 v10, 1.0
	s_cbranch_vccnz .LBB0_81
.LBB0_81:
	v_add_u32_e32 v9, 0x2020, v12
	v_add_u32_e32 v11, v34, v9
	s_waitcnt vmcnt(0)
	v_mov_b32_e32 v10, v66
	v_mul_f32_e32 v4, v4, v10
	v_lshl_add_u32 v12, v28, 2, v11
	ds_write_b32 v12, v4
	v_mul_f32_e32 v4, v5, v10
	v_lshl_add_u32 v5, v29, 2, v11
	ds_write_b32 v5, v4
	v_mul_f32_e32 v4, v6, v10
	v_lshl_add_u32 v5, v30, 2, v11
	ds_write_b32 v5, v4
	v_mul_f32_e32 v4, v7, v10
	v_lshl_add_u32 v5, v31, 2, v11
	s_and_b64 vcc, exec, s[4:5]
	ds_write_b32 v5, v4
	s_cbranch_vccnz .LBB0_46
	s_branch .LBB0_46
